# GU last iteration: ssq loads issued before the segment's DMAs; epilogue waits with vmcnt(6) so it no longer blocks on the next unit's prefetch DMAs
# speedup vs baseline: 1.0017x; 1.0017x over previous
; #define PG8_STAGE(bufoff, gbase, voff) do { _Pragma("unroll") for (int _i = 0; _i < 2; ++_i) \
;         __builtin_amdgcn_global_load_lds((const unsigned*)((const char*)(gbase) + (voff)[_i]), (PG8_LAS unsigned*)(lds + (bufoff) + ldsw + _i * 8192), 16, 0, 0); } while (0)
; #define PG8_LDA(dst, b, h) do { _Pragma("unroll") for (int m = 0; m < 4; ++m) _Pragma("unroll") for (int k = 0; k < 2; ++k) dst[m][k] = *(const PG8_LAS bf16x8*)(lds + PG8_SA(b, h) + aoff + m * 2048 + k * 1024); } while (0)
; #define PG8_LDB(dst, b, h) do { _Pragma("unroll") for (int n = 0; n < 2; ++n) _Pragma("unroll") for (int k = 0; k < 2; ++k) dst[n][k] = *(const PG8_LAS bf16x8*)(lds + PG8_SB(b, h) + boff + n * 2048 + k * 1024); } while (0)
; #define PG8_MMA(ai, bj, At, Bt) do { __builtin_amdgcn_s_setprio(1); _Pragma("unroll") for (int m = 0; m < 4; ++m) _Pragma("unroll") for (int n = 0; n < 2; ++n) _Pragma("unroll") for (int k = 0; k < 2; ++k) \
;         acc[ai][bj][m][n] = __builtin_amdgcn_mfma_f32_16x16x32_bf16(Bt[n][k], At[m][k], acc[ai][bj][m][n], 0, 0, 0); __builtin_amdgcn_s_setprio(0); } while (0)
; #define PG8_WAIT_V(n) asm volatile("s_waitcnt vmcnt(" #n ")" ::: "memory")
; #define PG8_WAIT_L(n) asm volatile("s_waitcnt lgkmcnt(" #n ")" ::: "memory")
; #define PG8_BAR __builtin_amdgcn_s_barrier()
; #define PG8_SCHED __builtin_amdgcn_sched_barrier(0)
;     __device__ __forceinline__ void operator()(const f32x4 (&acc)[2][2][4][2], const Unit& u, int wr, int wc, int fr, int fq) const {
;     ...
;             for (int m = 0; m < 4; ++m) sv[ai][m] = ssq[row0 + ai * HALF + m * 16];
; template <class Epi, class Sched, bool ALIGN_EPI = false, bool SP2 = true>
; __device__ __forceinline__ void gemm_phase(PG8_LAS unsigned char* lds, const Gemm g, const Sched& S, const Epi& E) {
;     ...
;             PG8_LDB(B0, 1, 0); PG8_LDB(B1, 1, 1); PG8_SCHED; PG8_LDA(At, 1, 0); PG8_STAGE(PG8_SA(0, 1), a2 + hstepA, voffA);
;             PG8_WAIT_V(8); PG8_WAIT_L(0); PG8_BAR; PG8_MMA(0, 0, At, B0); PG8_MMA(0, 1, At, B1); PG8_BAR; PG8_SCHED;
;             PG8_LDA(At, 1, 1); PG8_STAGE(PG8_SB(1, 0), b3, voffB); PG8_STAGE(PG8_SB(1, 1), b3 + hstep, voffB); PG8_STAGE(PG8_SA(1, 0), a3, voffA);
;             PG8_WAIT_V(8); PG8_WAIT_L(0); PG8_BAR; PG8_MMA(1, 0, At, B0); PG8_MMA(1, 1, At, B1); PG8_BAR; PG8_SCHED;
.Lgu_s3:
	s_add_i32 s70, 0, 0x18000
	v_add_u32_e32 v141, s70, v147
	s_add_i32 s71, 0, 0x1c000
	ds_read_b128 v[152:155], v141
	ds_read_b128 v[156:159], v141 offset:1024
	ds_read_b128 v[160:163], v141 offset:2048
	ds_read_b128 v[164:167], v141 offset:3072
	v_add_u32_e32 v141, s71, v147
	ds_read_b128 v[168:171], v141
	ds_read_b128 v[172:175], v141 offset:1024
	ds_read_b128 v[176:179], v141 offset:2048
	ds_read_b128 v[180:183], v141 offset:3072
	s_add_u32 s14, s48, 0x40000
	s_addc_u32 s15, s49, 0
	s_add_i32 m0, s28, 0x14000
	v_lshl_add_u64 v[236:237], s[14:15], 0, v[132:133]
	ds_read_b128 v[184:187], v150 offset:32768
	ds_read_b128 v[188:191], v150 offset:33792
	ds_read_b128 v[200:203], v150 offset:34816
	ds_read_b128 v[204:207], v150 offset:35840
	ds_read_b128 v[208:211], v150 offset:36864
	ds_read_b128 v[212:215], v150 offset:37888
	ds_read_b128 v[216:219], v150 offset:38912
	ds_read_b128 v[220:223], v150 offset:39936
	global_load_lds_dwordx4 v[236:237], off
	v_lshl_add_u64 v[236:237], s[14:15], 0, v[128:129]
	s_add_i32 m0, s28, 0x16000
	s_add_u32 s14, s50, 0x40000
	s_addc_u32 s15, s51, 0
	global_load_lds_dwordx4 v[236:237], off
	v_lshl_add_u64 v[236:237], s[14:15], 0, v[134:135]
	s_mov_b32 m0, s31
	s_nop 0
	global_load_lds_dwordx4 v[236:237], off
	v_lshl_add_u64 v[236:237], s[14:15], 0, v[130:131]
	s_mov_b32 m0, s34
	s_nop 0
	global_load_lds_dwordx4 v[236:237], off
	s_waitcnt vmcnt(8)
	s_waitcnt lgkmcnt(0)
	s_setprio 1
	s_barrier
	v_mfma_f32_16x16x32_bf16 v[120:123], v[152:155], v[184:187], v[120:123]
	v_mfma_f32_16x16x32_bf16 v[112:115], v[160:163], v[184:187], v[112:115]
	v_mfma_f32_16x16x32_bf16 v[108:111], v[152:155], v[200:203], v[108:111]
	v_mfma_f32_16x16x32_bf16 v[96:99], v[160:163], v[200:203], v[96:99]
	v_mfma_f32_16x16x32_bf16 v[92:95], v[152:155], v[208:211], v[92:95]
	v_mfma_f32_16x16x32_bf16 v[80:83], v[160:163], v[208:211], v[80:83]
	v_mfma_f32_16x16x32_bf16 v[76:79], v[152:155], v[216:219], v[76:79]
	v_mfma_f32_16x16x32_bf16 v[64:67], v[160:163], v[216:219], v[64:67]
	v_mfma_f32_16x16x32_bf16 v[120:123], v[156:159], v[188:191], v[120:123]
	v_mfma_f32_16x16x32_bf16 v[112:115], v[164:167], v[188:191], v[112:115]
	v_mfma_f32_16x16x32_bf16 v[108:111], v[156:159], v[204:207], v[108:111]
	v_mfma_f32_16x16x32_bf16 v[96:99], v[164:167], v[204:207], v[96:99]
	v_mfma_f32_16x16x32_bf16 v[92:95], v[156:159], v[212:215], v[92:95]
	v_mfma_f32_16x16x32_bf16 v[80:83], v[164:167], v[212:215], v[80:83]
	v_mfma_f32_16x16x32_bf16 v[76:79], v[156:159], v[220:223], v[76:79]
	v_mfma_f32_16x16x32_bf16 v[64:67], v[164:167], v[220:223], v[64:67]
	v_mfma_f32_16x16x32_bf16 v[124:127], v[168:171], v[184:187], v[124:127]
	v_mfma_f32_16x16x32_bf16 v[116:119], v[176:179], v[184:187], v[116:119]
	v_mfma_f32_16x16x32_bf16 v[104:107], v[168:171], v[200:203], v[104:107]
	v_mfma_f32_16x16x32_bf16 v[100:103], v[176:179], v[200:203], v[100:103]
	v_mfma_f32_16x16x32_bf16 v[88:91], v[168:171], v[208:211], v[88:91]
	v_mfma_f32_16x16x32_bf16 v[84:87], v[176:179], v[208:211], v[84:87]
	v_mfma_f32_16x16x32_bf16 v[72:75], v[168:171], v[216:219], v[72:75]
	v_mfma_f32_16x16x32_bf16 v[68:71], v[176:179], v[216:219], v[68:71]
	v_mfma_f32_16x16x32_bf16 v[124:127], v[172:175], v[188:191], v[124:127]
	v_mfma_f32_16x16x32_bf16 v[116:119], v[180:183], v[188:191], v[116:119]
	v_mfma_f32_16x16x32_bf16 v[104:107], v[172:175], v[204:207], v[104:107]
	v_mfma_f32_16x16x32_bf16 v[100:103], v[180:183], v[204:207], v[100:103]
	v_mfma_f32_16x16x32_bf16 v[88:91], v[172:175], v[212:215], v[88:91]
	v_mfma_f32_16x16x32_bf16 v[84:87], v[180:183], v[212:215], v[84:87]
	v_mfma_f32_16x16x32_bf16 v[72:75], v[172:175], v[220:223], v[72:75]
	v_mfma_f32_16x16x32_bf16 v[68:71], v[180:183], v[220:223], v[68:71]
	s_setprio 0
	s_barrier
	s_cmp_lg_u32 s60, 12
	s_cbranch_scc1 .Lgu_s4_notlast_a
	v_lshl_add_u32 v228, s58, 8, v145
	v_ashrrev_i32_e32 v229, 31, v228
	v_lshl_add_u64 v[228:229], v[228:229], 3, s[10:11]
	global_load_dwordx2 v[238:239], v[228:229], off
	global_load_dwordx2 v[240:241], v[228:229], off offset:128
	global_load_dwordx2 v[242:243], v[228:229], off offset:256
	global_load_dwordx2 v[244:245], v[228:229], off offset:384
	global_load_dwordx2 v[246:247], v[228:229], off offset:1024
	global_load_dwordx2 v[248:249], v[228:229], off offset:1152
	global_load_dwordx2 v[250:251], v[228:229], off offset:1280
	s_nop 0
	global_load_dwordx2 v[228:229], v[228:229], off offset:1408
.Lgu_s4_notlast_a:
	s_add_i32 s14, s70, s28
	v_lshl_add_u64 v[148:149], v[148:149], 0, s[18:19]
	s_mov_b32 m0, s14
	ds_read_b128 v[184:187], v150 offset:49152
	ds_read_b128 v[188:191], v150 offset:50176
	ds_read_b128 v[200:203], v150 offset:51200
	ds_read_b128 v[204:207], v150 offset:52224
	ds_read_b128 v[208:211], v150 offset:53248
	ds_read_b128 v[212:215], v150 offset:54272
	ds_read_b128 v[216:219], v150 offset:55296
	ds_read_b128 v[220:223], v150 offset:56320
	global_load_lds_dwordx4 v[148:149], off
	s_add_i32 m0, s14, 0x2000
	v_lshl_add_u64 v[148:149], v[224:225], 0, s[18:19]
	global_load_lds_dwordx4 v[148:149], off
	v_lshl_add_u64 v[148:149], v[226:227], 0, s[18:19]
	s_mov_b32 m0, s52
	s_nop 0
	global_load_lds_dwordx4 v[148:149], off
	v_lshl_add_u64 v[148:149], v[234:235], 0, s[18:19]
	s_mov_b32 m0, s53
	s_nop 0
	global_load_lds_dwordx4 v[148:149], off
	s_cmp_lg_u32 s60, 12
	s_cbranch_scc1 .Lgu_s4_w6
	s_waitcnt vmcnt(14)
	s_branch .Lgu_s4_wj

; #define PG8_STAGE(bufoff, gbase, voff) do { _Pragma("unroll") for (int _i = 0; _i < 2; ++_i) \
;         __builtin_amdgcn_global_load_lds((const unsigned*)((const char*)(gbase) + (voff)[_i]), (PG8_LAS unsigned*)(lds + (bufoff) + ldsw + _i * 8192), 16, 0, 0); } while (0)
; #define PG8_LDA(dst, b, h) do { _Pragma("unroll") for (int m = 0; m < 4; ++m) _Pragma("unroll") for (int k = 0; k < 2; ++k) dst[m][k] = *(const PG8_LAS bf16x8*)(lds + PG8_SA(b, h) + aoff + m * 2048 + k * 1024); } while (0)
; #define PG8_LDB(dst, b, h) do { _Pragma("unroll") for (int n = 0; n < 2; ++n) _Pragma("unroll") for (int k = 0; k < 2; ++k) dst[n][k] = *(const PG8_LAS bf16x8*)(lds + PG8_SB(b, h) + boff + n * 2048 + k * 1024); } while (0)
; #define PG8_WAIT_V(n) asm volatile("s_waitcnt vmcnt(" #n ")" ::: "memory")
; #define PG8_WAIT_L(n) asm volatile("s_waitcnt lgkmcnt(" #n ")" ::: "memory")
; #define PG8_BAR __builtin_amdgcn_s_barrier()
; #define PG8_SCHED __builtin_amdgcn_sched_barrier(0)
; template <class Epi, class Sched, bool ALIGN_EPI = false, bool SP2 = true>
; __device__ __forceinline__ void gemm_phase(PG8_LAS unsigned char* lds, const Gemm g, const Sched& S, const Epi& E) {
;     ...
;             if (last && has_next) S.a_ready(nxt);
;             if constexpr (SP2) {
;             PG8_LDB(B0, 0, 0); PG8_LDB(B1, 0, 1); PG8_SCHED; PG8_LDA(At, 0, 0); PG8_STAGE(PG8_SA(1, 1), a1 + hstepA, voffA);
;             PG8_WAIT_V(8); PG8_WAIT_L(0); PG8_BAR; PG8_MMA(0, 0, At, B0); PG8_MMA(0, 1, At, B1); PG8_BAR; PG8_SCHED;
;             PG8_LDA(At, 0, 1); PG8_STAGE(PG8_SB(0, 0), b2, voffB); PG8_STAGE(PG8_SB(0, 1), b2 + hstep, voffB); PG8_STAGE(PG8_SA(0, 0), a2, voffA);
;             PG8_WAIT_V(8); PG8_WAIT_L(0); PG8_BAR; PG8_MMA(1, 0, At, B0); PG8_MMA(1, 1, At, B1); PG8_BAR; PG8_SCHED;
;             PG8_LDB(B0, 1, 0); PG8_LDB(B1, 1, 1); PG8_SCHED; PG8_LDA(At, 1, 0); PG8_STAGE(PG8_SA(0, 1), a2 + hstepA, voffA);
;             PG8_WAIT_V(8); PG8_WAIT_L(0); PG8_BAR; PG8_MMA(0, 0, At, B0); PG8_MMA(0, 1, At, B1); PG8_BAR; PG8_SCHED;
;             PG8_LDA(At, 1, 1); PG8_STAGE(PG8_SB(1, 0), b3, voffB); PG8_STAGE(PG8_SB(1, 1), b3 + hstep, voffB); PG8_STAGE(PG8_SA(1, 0), a3, voffA);
;             PG8_WAIT_V(8); PG8_WAIT_L(0); PG8_BAR; PG8_MMA(1, 0, At, B0); PG8_MMA(1, 1, At, B1); PG8_BAR; PG8_SCHED;
.Lgu_s4_wj:
	s_waitcnt lgkmcnt(0)
	s_cmp_lg_u32 s60, 12
	s_cbranch_scc1 .Lgu_no_ssq_prefetch
	s_add_u32 s14, s48, 0x40080
	s_addc_u32 s15, s49, 0
	v_lshl_add_u64 v[148:149], s[14:15], 0, v[132:133]
	s_add_i32 m0, s28, 0x1c000
	s_nop 0
	global_load_lds_dwordx4 v[148:149], off
	v_lshl_add_u64 v[148:149], s[14:15], 0, v[128:129]
	s_add_i32 m0, s28, 0x1e000
	s_nop 0
	global_load_lds_dwordx4 v[148:149], off

; __device__ __forceinline__ float ssq_rs(ssq_t v) { return __builtin_amdgcn_rsqf((float)v * (1.0f / (16777216.0f * 1024.0f)) + RMS_EPS); }
;     __device__ __forceinline__ void operator()(const f32x4 (&acc)[2][2][4][2], const Unit& u, int wr, int wc, int fr, int fq) const {
;         const int row0 = u.pm * BM + wr * 64 + fr, col0 = u.pn * HALF + wc * 32 + 8 * fq;
;         float rsv[2][4]; ssq_t sv[2][4];
; #pragma unroll
;         for (int ai = 0; ai < 2; ++ai)
; #pragma unroll
;             for (int m = 0; m < 4; ++m) sv[ai][m] = ssq[row0 + ai * HALF + m * 16];
; #pragma unroll
;         for (int ai = 0; ai < 2; ++ai)
; #pragma unroll
;             for (int m = 0; m < 4; ++m) rsv[ai][m] = ssq_rs(sv[ai][m]);
;         asm volatile("" ::: "memory");
; #pragma unroll
;         for (int ai = 0; ai < 2; ++ai)
; #pragma unroll
;             for (int m = 0; m < 4; ++m) {
;                 const int row = row0 + ai * HALF + m * 16;
;                 const float rs = rsv[ai][m], nrs = rs * -1.44269504089f, rs2 = rs * rs;
;                 typedef float f32x2 __attribute__((ext_vector_type(2)));
;                 float a[8];
; #pragma unroll
;                 for (int n = 0; n < 2; ++n)
; #pragma unroll
;                     for (int hf = 0; hf < 2; ++hf) {
;                         const f32x2 g2 = (f32x2){acc[ai][0][m][n][2 * hf], acc[ai][0][m][n][2 * hf + 1]}, u2 = (f32x2){acc[ai][1][m][n][2 * hf], acc[ai][1][m][n][2 * hf + 1]};
;                         const f32x2 t = g2 * nrs;
;                         f32x2 e; e.x = __builtin_amdgcn_exp2f(t.x); e.y = __builtin_amdgcn_exp2f(t.y);
;                         const f32x2 d = e + 1.0f;
;                         f32x2 r; r.x = __builtin_amdgcn_rcpf(d.x); r.y = __builtin_amdgcn_rcpf(d.y);
;                         const f32x2 o = (g2 * u2) * (r * rs2);
.LBB0_131:
	v_add_u32_e32 v141, 0x14000, v147
	ds_read_b128 v[168:171], v141
	ds_read_b128 v[172:175], v141 offset:1024
	ds_read_b128 v[176:179], v141 offset:2048
	ds_read_b128 v[180:183], v141 offset:3072
	ds_read_b128 v[184:187], v150
	ds_read_b128 v[188:191], v150 offset:1024
	ds_read_b128 v[200:203], v150 offset:2048
	ds_read_b128 v[204:207], v150 offset:3072
	ds_read_b128 v[208:211], v150 offset:4096
	ds_read_b128 v[212:215], v150 offset:5120
	ds_read_b128 v[216:219], v150 offset:6144
	ds_read_b128 v[220:223], v150 offset:7168
	v_pk_mul_f32 v[126:127], v[122:123], v[126:127]
	v_pk_mul_f32 v[118:119], v[114:115], v[118:119]
	s_lshl_b32 s6, s16, 7
	s_or_b32 s6, s6, s35
	s_ashr_i32 s6, s6, 6
	s_mul_i32 s7, s58, 44
	s_add_i32 s6, s6, s7
	s_ashr_i32 s7, s6, 31
	s_lshl_b64 s[6:7], s[6:7], 15
	s_add_u32 s46, s62, s6
	s_addc_u32 s47, s63, s7
	v_pk_mul_f32 v[104:105], v[108:109], v[104:105]
	v_pk_mul_f32 v[106:107], v[110:111], v[106:107]
	v_pk_mul_f32 v[102:103], v[98:99], v[102:103]
	v_pk_mul_f32 v[88:89], v[92:93], v[88:89]
	v_pk_mul_f32 v[90:91], v[94:95], v[90:91]
	v_pk_mul_f32 v[86:87], v[82:83], v[86:87]
	v_pk_mul_f32 v[72:73], v[76:77], v[72:73]
	v_pk_mul_f32 v[74:75], v[78:79], v[74:75]
	v_pk_mul_f32 v[70:71], v[66:67], v[70:71]
	v_pk_mul_f32 v[56:57], v[60:61], v[56:57]
	v_pk_mul_f32 v[58:59], v[62:63], v[58:59]
	v_pk_mul_f32 v[54:55], v[50:51], v[54:55]
	v_pk_mul_f32 v[40:41], v[44:45], v[40:41]
	v_pk_mul_f32 v[42:43], v[46:47], v[42:43]
	v_pk_mul_f32 v[38:39], v[34:35], v[38:39]
	v_pk_mul_f32 v[24:25], v[28:29], v[24:25]
	v_pk_mul_f32 v[26:27], v[30:31], v[26:27]
	v_pk_mul_f32 v[22:23], v[18:19], v[22:23]
	v_pk_mul_f32 v[8:9], v[12:13], v[8:9]
	v_pk_mul_f32 v[10:11], v[14:15], v[10:11]
	v_pk_mul_f32 v[0:1], v[4:5], v[0:1]
	v_pk_mul_f32 v[2:3], v[6:7], v[2:3]
	s_waitcnt vmcnt(6)
	v_mov_b32_e32 v152, v238
	v_mov_b32_e32 v153, v239
	v_mov_b32_e32 v154, v240
	v_mov_b32_e32 v155, v241
	v_mov_b32_e32 v158, v242
	v_mov_b32_e32 v159, v243
	v_mov_b32_e32 v160, v244
	v_mov_b32_e32 v161, v245
	v_mov_b32_e32 v162, v246
	v_mov_b32_e32 v163, v247
	v_mov_b32_e32 v164, v248
	v_mov_b32_e32 v165, v249
	v_mov_b32_e32 v166, v250
	v_mov_b32_e32 v167, v251
	v_mov_b32_e32 v148, v228
	v_mov_b32_e32 v149, v229
	v_ffbh_u32_e32 v141, v153
	v_min_u32_e32 v141, 32, v141
	v_lshlrev_b64 v[152:153], v141, v[152:153]
	v_min_u32_e32 v143, 1, v152
	v_or_b32_e32 v143, v153, v143
	v_cvt_f32_u32_e32 v143, v143
	v_sub_u32_e32 v141, 32, v141
	v_ldexp_f32 v141, v143, v141
	v_ffbh_u32_e32 v143, v155
	v_min_u32_e32 v143, 32, v143
	v_lshlrev_b64 v[152:153], v143, v[154:155]
	v_min_u32_e32 v144, 1, v152
	v_or_b32_e32 v144, v153, v144
	v_cvt_f32_u32_e32 v144, v144
	v_sub_u32_e32 v143, 32, v143
	v_fmamk_f32 v141, v141, 0x2e800000, v193
	v_rsq_f32_e32 v141, v141
	v_ldexp_f32 v143, v144, v143
	v_fmamk_f32 v143, v143, 0x2e800000, v193
	v_rsq_f32_e32 v156, v143
	v_ffbh_u32_e32 v143, v159
	v_min_u32_e32 v143, 32, v143
	v_lshlrev_b64 v[152:153], v143, v[158:159]
	v_min_u32_e32 v144, 1, v152
	v_or_b32_e32 v144, v153, v144
	v_cvt_f32_u32_e32 v144, v144
	v_sub_u32_e32 v143, 32, v143
	v_ldexp_f32 v143, v144, v143
	v_fmamk_f32 v143, v143, 0x2e800000, v193
	v_rsq_f32_e32 v155, v143
	v_ffbh_u32_e32 v143, v161
	v_min_u32_e32 v143, 32, v143
	v_lshlrev_b64 v[152:153], v143, v[160:161]
	v_min_u32_e32 v144, 1, v152
	v_or_b32_e32 v144, v153, v144
	v_cvt_f32_u32_e32 v144, v144
	v_sub_u32_e32 v143, 32, v143
	v_ldexp_f32 v143, v144, v143
	v_fmamk_f32 v143, v143, 0x2e800000, v193
	v_rsq_f32_e32 v154, v143
	v_ffbh_u32_e32 v143, v163
	v_min_u32_e32 v143, 32, v143
	v_lshlrev_b64 v[152:153], v143, v[162:163]
	v_min_u32_e32 v144, 1, v152
	v_or_b32_e32 v144, v153, v144
	v_cvt_f32_u32_e32 v144, v144
	v_sub_u32_e32 v143, 32, v143
	v_ldexp_f32 v143, v144, v143
	v_ffbh_u32_e32 v144, v165
	v_min_u32_e32 v144, 32, v144
	v_lshlrev_b64 v[152:153], v144, v[164:165]
	v_min_u32_e32 v146, 1, v152
	v_or_b32_e32 v146, v153, v146
	v_cvt_f32_u32_e32 v146, v146
	v_sub_u32_e32 v144, 32, v144
	v_fmamk_f32 v143, v143, 0x2e800000, v193
	v_rsq_f32_e32 v143, v143
	v_ldexp_f32 v144, v146, v144
	v_fmamk_f32 v144, v144, 0x2e800000, v193
	v_rsq_f32_e32 v153, v144
	v_ffbh_u32_e32 v144, v167
	v_min_u32_e32 v144, 32, v144
	v_lshlrev_b64 v[158:159], v144, v[166:167]
	v_min_u32_e32 v146, 1, v158
	v_or_b32_e32 v146, v159, v146
	v_cvt_f32_u32_e32 v146, v146
	v_sub_u32_e32 v144, 32, v144
	v_ldexp_f32 v144, v146, v144
	v_fmamk_f32 v144, v144, 0x2e800000, v193
	v_rsq_f32_e32 v152, v144
	v_ffbh_u32_e32 v144, v149
	v_min_u32_e32 v144, 32, v144
	v_lshlrev_b64 v[148:149], v144, v[148:149]
	v_min_u32_e32 v146, 1, v148
	v_or_b32_e32 v146, v149, v146
	v_cvt_f32_u32_e32 v146, v146
	v_sub_u32_e32 v144, 32, v144
	v_ldexp_f32 v144, v146, v144
	v_mul_f32_e32 v146, 0xbfb8aa3b, v141
	v_pk_mul_f32 v[148:149], v[120:121], v[146:147] op_sel_hi:[1,0]
	v_fmamk_f32 v144, v144, 0x2e800000, v193
	v_exp_f32_e32 v148, v148
	v_exp_f32_e32 v149, v149
	v_rsq_f32_e32 v151, v144
	v_mul_f32_e32 v144, v141, v141
	v_pk_mul_f32 v[120:121], v[120:121], v[124:125]
	v_pk_add_f32 v[148:149], v[148:149], 1.0 op_sel_hi:[1,0]
	v_pk_mul_f32 v[122:123], v[122:123], v[146:147] op_sel_hi:[1,0]
	v_rcp_f32_e32 v148, v148
	v_rcp_f32_e32 v149, v149
	v_pk_mul_f32 v[114:115], v[114:115], v[146:147] op_sel_hi:[1,0]
	v_exp_f32_e32 v122, v122
	v_exp_f32_e32 v123, v123
	v_pk_mul_f32 v[124:125], v[144:145], v[148:149] op_sel_hi:[0,1]
	v_pk_mul_f32 v[120:121], v[120:121], v[124:125]
	v_pk_mul_f32 v[124:125], v[112:113], v[146:147] op_sel_hi:[1,0]
	v_exp_f32_e32 v114, v114
	v_exp_f32_e32 v124, v124
	v_exp_f32_e32 v125, v125
	v_exp_f32_e32 v115, v115
	v_pk_add_f32 v[122:123], v[122:123], 1.0 op_sel_hi:[1,0]
; __device__ __forceinline__ unsigned cvt_pk_bf16(float lo, float hi) { unsigned r; asm volatile("v_cvt_pk_bf16_f32 %0, %1, %2" : "=v"(r) : "v"(lo), "v"(hi)); return r; }
;     __device__ __forceinline__ void operator()(const f32x4 (&acc)[2][2][4][2], const Unit& u, int wr, int wc, int fr, int fq) const {
;     ...
;             for (int m = 0; m < 4; ++m) {
;                 const int row = row0 + ai * HALF + m * 16;
;                 const float rs = rsv[ai][m], nrs = rs * -1.44269504089f, rs2 = rs * rs;
;                 typedef float f32x2 __attribute__((ext_vector_type(2)));
;                 float a[8];
; #pragma unroll
;                 for (int n = 0; n < 2; ++n)
; #pragma unroll
;                     for (int hf = 0; hf < 2; ++hf) {
;                         const f32x2 g2 = (f32x2){acc[ai][0][m][n][2 * hf], acc[ai][0][m][n][2 * hf + 1]}, u2 = (f32x2){acc[ai][1][m][n][2 * hf], acc[ai][1][m][n][2 * hf + 1]};
;                         const f32x2 t = g2 * nrs;
;                         f32x2 e; e.x = __builtin_amdgcn_exp2f(t.x); e.y = __builtin_amdgcn_exp2f(t.y);
;                         const f32x2 d = e + 1.0f;
;                         f32x2 r; r.x = __builtin_amdgcn_rcpf(d.x); r.y = __builtin_amdgcn_rcpf(d.y);
;                         const f32x2 o = (g2 * u2) * (r * rs2);
;                         a[n * 4 + 2 * hf] = o.x; a[n * 4 + 2 * hf + 1] = o.y;
;                     }
;                 u32x4 w; w.x = cvt_pk_bf16(a[0], a[1]); w.y = cvt_pk_bf16(a[2], a[3]); w.z = cvt_pk_bf16(a[4], a[5]); w.w = cvt_pk_bf16(a[6], a[7]);
;                 __builtin_nontemporal_store(w, (u32x4*)(O + ((size_t)(u.pm * (ldc >> 6) + (col0 >> 6)) * 256 + (row & 255)) * 64 + (col0 & 63)));
	v_pk_mul_f32 v[112:113], v[112:113], v[116:117]
	v_pk_add_f32 v[124:125], v[124:125], 1.0 op_sel_hi:[1,0]
	v_pk_add_f32 v[114:115], v[114:115], 1.0 op_sel_hi:[1,0]
	v_rcp_f32_e32 v124, v124
	v_rcp_f32_e32 v125, v125
	v_rcp_f32_e32 v122, v122
	v_rcp_f32_e32 v123, v123
	v_rcp_f32_e32 v114, v114
	v_rcp_f32_e32 v115, v115
	v_pk_mul_f32 v[116:117], v[144:145], v[124:125] op_sel_hi:[0,1]
	v_pk_mul_f32 v[122:123], v[144:145], v[122:123] op_sel_hi:[0,1]
	v_pk_mul_f32 v[112:113], v[112:113], v[116:117]
	v_pk_mul_f32 v[114:115], v[144:145], v[114:115] op_sel_hi:[0,1]
	v_pk_mul_f32 v[122:123], v[126:127], v[122:123]
	v_pk_mul_f32 v[118:119], v[118:119], v[114:115]
	v_cvt_pk_bf16_f32 v114, v120, v121
	v_cvt_pk_bf16_f32 v115, v122, v123
	v_cvt_pk_bf16_f32 v116, v112, v113
	v_lshl_add_u64 v[112:113], s[46:47], 0, v[194:195]
	v_mov_b32_e32 v141, v195
	v_lshl_add_u64 v[112:113], v[112:113], 0, v[140:141]
	v_cvt_pk_bf16_f32 v117, v118, v119
	global_store_dwordx4 v[112:113], v[114:117], off nt
	s_nop 1
	v_mul_f32_e32 v114, 0xbfb8aa3b, v156
	v_pk_mul_f32 v[118:119], v[108:109], v[114:115] op_sel_hi:[1,0]
	v_mul_f32_e32 v116, v156, v156
	v_exp_f32_e32 v118, v118
	v_exp_f32_e32 v119, v119
	s_nop 0
	v_pk_add_f32 v[118:119], v[118:119], 1.0 op_sel_hi:[1,0]
	s_nop 0
	v_rcp_f32_e32 v118, v118
	v_rcp_f32_e32 v119, v119
	s_nop 0
	v_pk_mul_f32 v[108:109], v[116:117], v[118:119] op_sel_hi:[0,1]
	v_pk_mul_f32 v[104:105], v[104:105], v[108:109]
	v_pk_mul_f32 v[108:109], v[110:111], v[114:115] op_sel_hi:[1,0]
	s_nop 0
	v_exp_f32_e32 v108, v108
	v_exp_f32_e32 v109, v109
	s_nop 0
	v_pk_add_f32 v[108:109], v[108:109], 1.0 op_sel_hi:[1,0]
	s_nop 0
	v_rcp_f32_e32 v108, v108
	v_rcp_f32_e32 v109, v109
	s_nop 0
	v_pk_mul_f32 v[108:109], v[116:117], v[108:109] op_sel_hi:[0,1]
	v_pk_mul_f32 v[106:107], v[106:107], v[108:109]
	v_pk_mul_f32 v[108:109], v[96:97], v[114:115] op_sel_hi:[1,0]
	v_pk_mul_f32 v[96:97], v[96:97], v[100:101]
	v_exp_f32_e32 v108, v108
	v_exp_f32_e32 v109, v109
	s_nop 0
	v_pk_add_f32 v[108:109], v[108:109], 1.0 op_sel_hi:[1,0]
	s_nop 0
	v_rcp_f32_e32 v108, v108
	v_rcp_f32_e32 v109, v109
	s_nop 0
	v_pk_mul_f32 v[100:101], v[116:117], v[108:109] op_sel_hi:[0,1]
	v_pk_mul_f32 v[100:101], v[96:97], v[100:101]
	v_pk_mul_f32 v[96:97], v[98:99], v[114:115] op_sel_hi:[1,0]
	s_nop 0
	v_exp_f32_e32 v96, v96
	v_exp_f32_e32 v97, v97
	s_nop 0
	v_pk_add_f32 v[96:97], v[96:97], 1.0 op_sel_hi:[1,0]
	s_nop 0
	v_rcp_f32_e32 v96, v96
	v_rcp_f32_e32 v97, v97
	s_nop 0
	v_pk_mul_f32 v[96:97], v[116:117], v[96:97] op_sel_hi:[0,1]
	v_pk_mul_f32 v[102:103], v[102:103], v[96:97]
	v_cvt_pk_bf16_f32 v96, v104, v105
	v_cvt_pk_bf16_f32 v97, v106, v107
	v_cvt_pk_bf16_f32 v98, v100, v101
	s_nop 0
	v_cvt_pk_bf16_f32 v99, v102, v103
	global_store_dwordx4 v[112:113], v[96:99], off offset:2048 nt
	s_nop 1
	v_mul_f32_e32 v96, 0xbfb8aa3b, v155
	v_pk_mul_f32 v[100:101], v[92:93], v[96:97] op_sel_hi:[1,0]
	v_mul_f32_e32 v98, v155, v155
	v_exp_f32_e32 v100, v100
	v_exp_f32_e32 v101, v101
	s_nop 0
	v_pk_add_f32 v[100:101], v[100:101], 1.0 op_sel_hi:[1,0]
	s_nop 0
	v_rcp_f32_e32 v100, v100
	v_rcp_f32_e32 v101, v101
	s_nop 0
	v_pk_mul_f32 v[92:93], v[98:99], v[100:101] op_sel_hi:[0,1]
	v_pk_mul_f32 v[88:89], v[88:89], v[92:93]
	v_pk_mul_f32 v[92:93], v[94:95], v[96:97] op_sel_hi:[1,0]
	s_nop 0
	v_exp_f32_e32 v92, v92
	v_exp_f32_e32 v93, v93
	s_nop 0
	v_pk_add_f32 v[92:93], v[92:93], 1.0 op_sel_hi:[1,0]
	s_nop 0
	v_rcp_f32_e32 v92, v92
	v_rcp_f32_e32 v93, v93
	s_nop 0
	v_pk_mul_f32 v[92:93], v[98:99], v[92:93] op_sel_hi:[0,1]
	v_pk_mul_f32 v[90:91], v[90:91], v[92:93]
	v_pk_mul_f32 v[92:93], v[80:81], v[96:97] op_sel_hi:[1,0]
	v_pk_mul_f32 v[80:81], v[80:81], v[84:85]
	v_exp_f32_e32 v92, v92
	v_exp_f32_e32 v93, v93
	s_nop 0
	v_pk_add_f32 v[92:93], v[92:93], 1.0 op_sel_hi:[1,0]
	s_nop 0
	v_rcp_f32_e32 v92, v92
	v_rcp_f32_e32 v93, v93
	s_nop 0
	v_pk_mul_f32 v[84:85], v[98:99], v[92:93] op_sel_hi:[0,1]
	v_pk_mul_f32 v[84:85], v[80:81], v[84:85]
	v_pk_mul_f32 v[80:81], v[82:83], v[96:97] op_sel_hi:[1,0]
	s_nop 0
	v_exp_f32_e32 v80, v80
	v_exp_f32_e32 v81, v81
	s_nop 0
	v_pk_add_f32 v[80:81], v[80:81], 1.0 op_sel_hi:[1,0]
	s_nop 0
	v_rcp_f32_e32 v80, v80
	v_rcp_f32_e32 v81, v81
	s_nop 0
	v_pk_mul_f32 v[80:81], v[98:99], v[80:81] op_sel_hi:[0,1]
	v_pk_mul_f32 v[86:87], v[86:87], v[80:81]
	v_cvt_pk_bf16_f32 v80, v88, v89
	v_cvt_pk_bf16_f32 v81, v90, v91
	v_cvt_pk_bf16_f32 v82, v84, v85
	v_add_co_u32_e32 v84, vcc, s23, v112
	v_cvt_pk_bf16_f32 v83, v86, v87
	s_nop 1
	v_addc_co_u32_e32 v85, vcc, 0, v113, vcc
	global_store_dwordx4 v[84:85], v[80:83], off nt
	s_nop 1
	v_mul_f32_e32 v80, 0xbfb8aa3b, v154
	v_pk_mul_f32 v[86:87], v[76:77], v[80:81] op_sel_hi:[1,0]
	v_mul_f32_e32 v82, v154, v154
	v_exp_f32_e32 v86, v86
	v_exp_f32_e32 v87, v87
	s_nop 0
	v_pk_add_f32 v[86:87], v[86:87], 1.0 op_sel_hi:[1,0]
	s_nop 0
	v_rcp_f32_e32 v86, v86
	v_rcp_f32_e32 v87, v87
	s_nop 0
	v_pk_mul_f32 v[76:77], v[82:83], v[86:87] op_sel_hi:[0,1]
	v_pk_mul_f32 v[72:73], v[72:73], v[76:77]
	v_pk_mul_f32 v[76:77], v[78:79], v[80:81] op_sel_hi:[1,0]
	s_nop 0
	v_exp_f32_e32 v76, v76
	v_exp_f32_e32 v77, v77
	s_nop 0
	v_pk_add_f32 v[76:77], v[76:77], 1.0 op_sel_hi:[1,0]
	s_nop 0
	v_rcp_f32_e32 v76, v76
	v_rcp_f32_e32 v77, v77
	s_nop 0
	v_pk_mul_f32 v[76:77], v[82:83], v[76:77] op_sel_hi:[0,1]
	v_pk_mul_f32 v[74:75], v[74:75], v[76:77]
	v_pk_mul_f32 v[76:77], v[64:65], v[80:81] op_sel_hi:[1,0]
	v_pk_mul_f32 v[64:65], v[64:65], v[68:69]
	v_exp_f32_e32 v76, v76
	v_exp_f32_e32 v77, v77
	s_nop 0
	v_pk_add_f32 v[76:77], v[76:77], 1.0 op_sel_hi:[1,0]
	s_nop 0
	v_rcp_f32_e32 v76, v76
	v_rcp_f32_e32 v77, v77
	s_nop 0
	v_pk_mul_f32 v[68:69], v[82:83], v[76:77] op_sel_hi:[0,1]
; __device__ __forceinline__ unsigned cvt_pk_bf16(float lo, float hi) { unsigned r; asm volatile("v_cvt_pk_bf16_f32 %0, %1, %2" : "=v"(r) : "v"(lo), "v"(hi)); return r; }
;     __device__ __forceinline__ void operator()(const f32x4 (&acc)[2][2][4][2], const Unit& u, int wr, int wc, int fr, int fq) const {
;     ...
;             for (int m = 0; m < 4; ++m) {
;                 const int row = row0 + ai * HALF + m * 16;
;                 const float rs = rsv[ai][m], nrs = rs * -1.44269504089f, rs2 = rs * rs;
;                 typedef float f32x2 __attribute__((ext_vector_type(2)));
;                 float a[8];
; #pragma unroll
;                 for (int n = 0; n < 2; ++n)
; #pragma unroll
;                     for (int hf = 0; hf < 2; ++hf) {
;                         const f32x2 g2 = (f32x2){acc[ai][0][m][n][2 * hf], acc[ai][0][m][n][2 * hf + 1]}, u2 = (f32x2){acc[ai][1][m][n][2 * hf], acc[ai][1][m][n][2 * hf + 1]};
;                         const f32x2 t = g2 * nrs;
;                         f32x2 e; e.x = __builtin_amdgcn_exp2f(t.x); e.y = __builtin_amdgcn_exp2f(t.y);
;                         const f32x2 d = e + 1.0f;
;                         f32x2 r; r.x = __builtin_amdgcn_rcpf(d.x); r.y = __builtin_amdgcn_rcpf(d.y);
;                         const f32x2 o = (g2 * u2) * (r * rs2);
;                         a[n * 4 + 2 * hf] = o.x; a[n * 4 + 2 * hf + 1] = o.y;
;                     }
;                 u32x4 w; w.x = cvt_pk_bf16(a[0], a[1]); w.y = cvt_pk_bf16(a[2], a[3]); w.z = cvt_pk_bf16(a[4], a[5]); w.w = cvt_pk_bf16(a[6], a[7]);
;                 __builtin_nontemporal_store(w, (u32x4*)(O + ((size_t)(u.pm * (ldc >> 6) + (col0 >> 6)) * 256 + (row & 255)) * 64 + (col0 & 63)));
	v_pk_mul_f32 v[68:69], v[64:65], v[68:69]
	v_pk_mul_f32 v[64:65], v[66:67], v[80:81] op_sel_hi:[1,0]
	s_nop 0
	v_exp_f32_e32 v64, v64
	v_exp_f32_e32 v65, v65
	s_nop 0
	v_pk_add_f32 v[64:65], v[64:65], 1.0 op_sel_hi:[1,0]
	s_nop 0
	v_rcp_f32_e32 v64, v64
	v_rcp_f32_e32 v65, v65
	s_nop 0
	v_pk_mul_f32 v[64:65], v[82:83], v[64:65] op_sel_hi:[0,1]
	v_pk_mul_f32 v[70:71], v[70:71], v[64:65]
	v_cvt_pk_bf16_f32 v64, v72, v73
	v_cvt_pk_bf16_f32 v65, v74, v75
	v_cvt_pk_bf16_f32 v66, v68, v69
	s_nop 0
	v_cvt_pk_bf16_f32 v67, v70, v71
	global_store_dwordx4 v[84:85], v[64:67], off offset:2048 nt
	s_nop 1
	v_mul_f32_e32 v64, 0xbfb8aa3b, v143
	v_pk_mul_f32 v[68:69], v[60:61], v[64:65] op_sel_hi:[1,0]
	v_mul_f32_e32 v66, v143, v143
	v_exp_f32_e32 v68, v68
	v_exp_f32_e32 v69, v69
	v_pk_mul_f32 v[50:51], v[50:51], v[64:65] op_sel_hi:[1,0]
	v_mov_b32_e32 v143, v195
	v_exp_f32_e32 v50, v50
	v_pk_add_f32 v[68:69], v[68:69], 1.0 op_sel_hi:[1,0]
	v_exp_f32_e32 v51, v51
	v_rcp_f32_e32 v68, v68
	v_rcp_f32_e32 v69, v69
	v_pk_add_f32 v[50:51], v[50:51], 1.0 op_sel_hi:[1,0]
	s_nop 0
	v_rcp_f32_e32 v50, v50
	v_pk_mul_f32 v[60:61], v[66:67], v[68:69] op_sel_hi:[0,1]
	v_pk_mul_f32 v[56:57], v[56:57], v[60:61]
	v_pk_mul_f32 v[60:61], v[62:63], v[64:65] op_sel_hi:[1,0]
	v_rcp_f32_e32 v51, v51
	v_exp_f32_e32 v60, v60
	v_exp_f32_e32 v61, v61
	v_pk_mul_f32 v[50:51], v[66:67], v[50:51] op_sel_hi:[0,1]
	v_pk_mul_f32 v[54:55], v[54:55], v[50:51]
	v_pk_add_f32 v[60:61], v[60:61], 1.0 op_sel_hi:[1,0]
	v_cvt_pk_bf16_f32 v50, v56, v57
	s_nop 0
	v_rcp_f32_e32 v60, v60
	v_rcp_f32_e32 v61, v61
	s_nop 0
	v_pk_mul_f32 v[60:61], v[66:67], v[60:61] op_sel_hi:[0,1]
	v_pk_mul_f32 v[58:59], v[58:59], v[60:61]
	v_pk_mul_f32 v[60:61], v[48:49], v[64:65] op_sel_hi:[1,0]
	v_pk_mul_f32 v[48:49], v[48:49], v[52:53]
	v_exp_f32_e32 v60, v60
	v_exp_f32_e32 v61, v61
	v_cvt_pk_bf16_f32 v51, v58, v59
	s_nop 0
	v_pk_add_f32 v[60:61], v[60:61], 1.0 op_sel_hi:[1,0]
	s_nop 0
	v_rcp_f32_e32 v60, v60
	v_rcp_f32_e32 v61, v61
	s_nop 0
	v_pk_mul_f32 v[52:53], v[66:67], v[60:61] op_sel_hi:[0,1]
	v_pk_mul_f32 v[48:49], v[48:49], v[52:53]
	s_nop 0
	v_cvt_pk_bf16_f32 v52, v48, v49
	v_lshl_add_u64 v[48:49], s[46:47], 0, v[142:143]
	v_lshl_add_u64 v[48:49], v[48:49], 0, v[140:141]
	v_cvt_pk_bf16_f32 v53, v54, v55
	global_store_dwordx4 v[48:49], v[50:53], off nt
	s_mov_b64 s[46:47], -1
	s_nop 0
	v_mul_f32_e32 v50, 0xbfb8aa3b, v153
	v_pk_mul_f32 v[54:55], v[44:45], v[50:51] op_sel_hi:[1,0]
	v_mul_f32_e32 v52, v153, v153
	v_exp_f32_e32 v54, v54
	v_exp_f32_e32 v55, v55
	s_nop 0
	v_pk_add_f32 v[54:55], v[54:55], 1.0 op_sel_hi:[1,0]
	s_nop 0
	v_rcp_f32_e32 v54, v54
	v_rcp_f32_e32 v55, v55
	s_nop 0
	v_pk_mul_f32 v[44:45], v[52:53], v[54:55] op_sel_hi:[0,1]
	v_pk_mul_f32 v[40:41], v[40:41], v[44:45]
	v_pk_mul_f32 v[44:45], v[46:47], v[50:51] op_sel_hi:[1,0]
	s_nop 0
	v_exp_f32_e32 v44, v44
	v_exp_f32_e32 v45, v45
	s_nop 0
	v_pk_add_f32 v[44:45], v[44:45], 1.0 op_sel_hi:[1,0]
	s_nop 0
	v_rcp_f32_e32 v44, v44
	v_rcp_f32_e32 v45, v45
	s_nop 0
	v_pk_mul_f32 v[44:45], v[52:53], v[44:45] op_sel_hi:[0,1]
	v_pk_mul_f32 v[42:43], v[42:43], v[44:45]
	v_pk_mul_f32 v[44:45], v[32:33], v[50:51] op_sel_hi:[1,0]
	v_pk_mul_f32 v[32:33], v[32:33], v[36:37]
	v_exp_f32_e32 v44, v44
	v_exp_f32_e32 v45, v45
	s_nop 0
	v_pk_add_f32 v[44:45], v[44:45], 1.0 op_sel_hi:[1,0]
	s_nop 0
	v_rcp_f32_e32 v44, v44
	v_rcp_f32_e32 v45, v45
	s_nop 0
	v_pk_mul_f32 v[36:37], v[52:53], v[44:45] op_sel_hi:[0,1]
	v_pk_mul_f32 v[36:37], v[32:33], v[36:37]
	v_pk_mul_f32 v[32:33], v[34:35], v[50:51] op_sel_hi:[1,0]
	s_nop 0
	v_exp_f32_e32 v32, v32
	v_exp_f32_e32 v33, v33
	s_nop 0
	v_pk_add_f32 v[32:33], v[32:33], 1.0 op_sel_hi:[1,0]
	s_nop 0
	v_rcp_f32_e32 v32, v32
	v_rcp_f32_e32 v33, v33
	s_nop 0
	v_pk_mul_f32 v[32:33], v[52:53], v[32:33] op_sel_hi:[0,1]
; #define PG8_BAR __builtin_amdgcn_s_barrier()
;     __device__ __forceinline__ void operator()(const f32x4 (&acc)[2][2][4][2], const Unit& u, int wr, int wc, int fr, int fq) const {
;     ...
;             for (int m = 0; m < 4; ++m) {
;                 const int row = row0 + ai * HALF + m * 16;
;                 const float rs = rsv[ai][m], nrs = rs * -1.44269504089f, rs2 = rs * rs;
;                 typedef float f32x2 __attribute__((ext_vector_type(2)));
;                 float a[8];
; #pragma unroll
;                 for (int n = 0; n < 2; ++n)
; #pragma unroll
;                     for (int hf = 0; hf < 2; ++hf) {
;                         const f32x2 g2 = (f32x2){acc[ai][0][m][n][2 * hf], acc[ai][0][m][n][2 * hf + 1]}, u2 = (f32x2){acc[ai][1][m][n][2 * hf], acc[ai][1][m][n][2 * hf + 1]};
;                         const f32x2 t = g2 * nrs;
;                         f32x2 e; e.x = __builtin_amdgcn_exp2f(t.x); e.y = __builtin_amdgcn_exp2f(t.y);
;                         const f32x2 d = e + 1.0f;
;                         f32x2 r; r.x = __builtin_amdgcn_rcpf(d.x); r.y = __builtin_amdgcn_rcpf(d.y);
;                         const f32x2 o = (g2 * u2) * (r * rs2);
;                         a[n * 4 + 2 * hf] = o.x; a[n * 4 + 2 * hf + 1] = o.y;
;                     }
;                 u32x4 w; w.x = cvt_pk_bf16(a[0], a[1]); w.y = cvt_pk_bf16(a[2], a[3]); w.z = cvt_pk_bf16(a[4], a[5]); w.w = cvt_pk_bf16(a[6], a[7]);
;                 __builtin_nontemporal_store(w, (u32x4*)(O + ((size_t)(u.pm * (ldc >> 6) + (col0 >> 6)) * 256 + (row & 255)) * 64 + (col0 & 63)));
;             }
;     }
; template <class Epi, class Sched, bool ALIGN_EPI = false, bool SP2 = true>
; __device__ __forceinline__ void gemm_phase(PG8_LAS unsigned char* lds, const Gemm g, const Sched& S, const Epi& E) {
;     ...
;         if constexpr (ALIGN_EPI) { if (wr == 0) PG8_BAR; }
;         if constexpr (!Epi::AFTER_DRAIN) { E(acc, cur, wr, wc, fr, fq); S.done(cur); }
;         if (!has_next) break;
; #pragma unroll
;         for (int a = 0; a < 2; ++a)
; #pragma unroll
;             for (int b = 0; b < 2; ++b)
; #pragma unroll
;                 for (int m = 0; m < 4; ++m)
; #pragma unroll
;                     for (int n = 0; n < 2; ++n) acc[a][b][m][n] = (f32x4){0.f, 0.f, 0.f, 0.f};
;         cur = nxt; cA = nA; cB = nB; ++ui;
;         if constexpr (ALIGN_EPI) { if (wr == 1) PG8_BAR; }
;     }
	v_pk_mul_f32 v[38:39], v[38:39], v[32:33]
	v_cvt_pk_bf16_f32 v32, v40, v41
	v_cvt_pk_bf16_f32 v33, v42, v43
	v_cvt_pk_bf16_f32 v34, v36, v37
	s_nop 0
	v_cvt_pk_bf16_f32 v35, v38, v39
	global_store_dwordx4 v[48:49], v[32:35], off offset:2048 nt
	s_nop 1
	v_mul_f32_e32 v32, 0xbfb8aa3b, v152
	v_pk_mul_f32 v[36:37], v[28:29], v[32:33] op_sel_hi:[1,0]
	v_mul_f32_e32 v34, v152, v152
	v_exp_f32_e32 v36, v36
	v_exp_f32_e32 v37, v37
	s_nop 0
	v_pk_add_f32 v[36:37], v[36:37], 1.0 op_sel_hi:[1,0]
	s_nop 0
	v_rcp_f32_e32 v36, v36
	v_rcp_f32_e32 v37, v37
	s_nop 0
	v_pk_mul_f32 v[28:29], v[34:35], v[36:37] op_sel_hi:[0,1]
	v_pk_mul_f32 v[24:25], v[24:25], v[28:29]
	v_pk_mul_f32 v[28:29], v[30:31], v[32:33] op_sel_hi:[1,0]
	s_nop 0
	v_exp_f32_e32 v28, v28
	v_exp_f32_e32 v29, v29
	s_nop 0
	v_pk_add_f32 v[28:29], v[28:29], 1.0 op_sel_hi:[1,0]
	s_nop 0
	v_rcp_f32_e32 v28, v28
	v_rcp_f32_e32 v29, v29
	s_nop 0
	v_pk_mul_f32 v[28:29], v[34:35], v[28:29] op_sel_hi:[0,1]
	v_pk_mul_f32 v[26:27], v[26:27], v[28:29]
	v_pk_mul_f32 v[28:29], v[16:17], v[32:33] op_sel_hi:[1,0]
	v_pk_mul_f32 v[16:17], v[16:17], v[20:21]
	v_exp_f32_e32 v28, v28
	v_exp_f32_e32 v29, v29
	s_nop 0
	v_pk_add_f32 v[28:29], v[28:29], 1.0 op_sel_hi:[1,0]
	s_nop 0
	v_rcp_f32_e32 v28, v28
	v_rcp_f32_e32 v29, v29
	s_nop 0
	v_pk_mul_f32 v[20:21], v[34:35], v[28:29] op_sel_hi:[0,1]
	v_pk_mul_f32 v[20:21], v[16:17], v[20:21]
	v_pk_mul_f32 v[16:17], v[18:19], v[32:33] op_sel_hi:[1,0]
	s_nop 0
	v_exp_f32_e32 v16, v16
	v_exp_f32_e32 v17, v17
	s_nop 0
	v_pk_add_f32 v[16:17], v[16:17], 1.0 op_sel_hi:[1,0]
	s_nop 0
	v_rcp_f32_e32 v16, v16
	v_rcp_f32_e32 v17, v17
	s_nop 0
	v_pk_mul_f32 v[16:17], v[34:35], v[16:17] op_sel_hi:[0,1]
	v_pk_mul_f32 v[22:23], v[22:23], v[16:17]
	v_cvt_pk_bf16_f32 v16, v24, v25
	v_cvt_pk_bf16_f32 v17, v26, v27
	v_cvt_pk_bf16_f32 v18, v20, v21
	v_add_co_u32_e32 v20, vcc, s23, v48
	v_cvt_pk_bf16_f32 v19, v22, v23
	s_nop 1
	v_addc_co_u32_e32 v21, vcc, 0, v49, vcc
	global_store_dwordx4 v[20:21], v[16:19], off nt
	s_andn2_b64 vcc, exec, s[36:37]
	s_nop 0
	v_mul_f32_e32 v16, 0xbfb8aa3b, v151
	v_pk_mul_f32 v[22:23], v[12:13], v[16:17] op_sel_hi:[1,0]
	v_mul_f32_e32 v18, v151, v151
	v_exp_f32_e32 v22, v22
	v_exp_f32_e32 v23, v23
	s_nop 0
	v_pk_add_f32 v[22:23], v[22:23], 1.0 op_sel_hi:[1,0]
	s_nop 0
	v_rcp_f32_e32 v22, v22
	v_rcp_f32_e32 v23, v23
	s_nop 0
	v_pk_mul_f32 v[12:13], v[18:19], v[22:23] op_sel_hi:[0,1]
	v_pk_mul_f32 v[8:9], v[8:9], v[12:13]
	v_pk_mul_f32 v[12:13], v[14:15], v[16:17] op_sel_hi:[1,0]
	s_nop 0
	v_exp_f32_e32 v12, v12
	v_exp_f32_e32 v13, v13
	s_nop 0
	v_pk_add_f32 v[12:13], v[12:13], 1.0 op_sel_hi:[1,0]
	s_nop 0
	v_rcp_f32_e32 v12, v12
	v_rcp_f32_e32 v13, v13
	s_nop 0
	v_pk_mul_f32 v[12:13], v[18:19], v[12:13] op_sel_hi:[0,1]
	v_pk_mul_f32 v[10:11], v[10:11], v[12:13]
	v_pk_mul_f32 v[12:13], v[4:5], v[16:17] op_sel_hi:[1,0]
	s_nop 0
	v_exp_f32_e32 v12, v12
	v_exp_f32_e32 v13, v13
	s_nop 0
	v_pk_add_f32 v[12:13], v[12:13], 1.0 op_sel_hi:[1,0]
	s_nop 0
	v_rcp_f32_e32 v12, v12
	v_rcp_f32_e32 v13, v13
	s_nop 0
	v_pk_mul_f32 v[4:5], v[18:19], v[12:13] op_sel_hi:[0,1]
	v_pk_mul_f32 v[4:5], v[0:1], v[4:5]
	v_pk_mul_f32 v[0:1], v[6:7], v[16:17] op_sel_hi:[1,0]
	s_nop 0
	v_exp_f32_e32 v0, v0
	v_exp_f32_e32 v1, v1
	s_nop 0
	v_pk_add_f32 v[0:1], v[0:1], 1.0 op_sel_hi:[1,0]
	s_nop 0
	v_rcp_f32_e32 v0, v0
	v_rcp_f32_e32 v1, v1
	s_nop 0
	v_pk_mul_f32 v[0:1], v[18:19], v[0:1] op_sel_hi:[0,1]
	v_pk_mul_f32 v[6:7], v[2:3], v[0:1]
	v_cvt_pk_bf16_f32 v0, v8, v9
	v_cvt_pk_bf16_f32 v1, v10, v11
	v_cvt_pk_bf16_f32 v2, v4, v5
	s_nop 0
	v_cvt_pk_bf16_f32 v3, v6, v7
	global_store_dwordx4 v[20:21], v[0:3], off offset:2048 nt
	s_cbranch_vccnz .LBB0_124
	s_andn2_b64 vcc, exec, s[0:1]
	s_cbranch_vccnz .LBB0_123
	s_barrier
	s_branch .LBB0_123
